# v14 + worker-side: GLA a/c-tile f32 division replaced by rcp-refined sequence already validated earlier, grouped LDS reads in exp blocks
# speedup vs baseline: 1.0070x; 1.0064x over previous
; #define LAS __attribute__((address_space(3)))
; __device__ __forceinline__ unsigned cvt_pk_bf16(float lo, float hi) { const f32x2 v = {lo, hi}; const bf16x2_t r = __builtin_convertvector(v, bf16x2_t); return __builtin_bit_cast(unsigned, r); }
; __device__ __forceinline__ void gla_c_tile(LAS unsigned char* lds, const GlaArgs& A, int tile, int tid) {
;     ...
;       if (cc < 128) { const int d = cc & 63; const bool isq = cc < 64; LAS bf16_t* T1 = isq ? QG : KR; LAS bf16_t* T2 = isq ? QR : KG; const float sc = isq ? 0.125f : 1.0f;
; #pragma unroll
;           for (int e = 0; e < 8; ++e) { const int i = i0 + 8 * e; f32x4 x1, x2;
; #pragma unroll
;               for (int q = 0; q < 4; ++q) { const float eg = __expf(GC[i * 65 + d + q]); const float x = o[e][q] * sc; x1[q] = x * eg; x2[q] = x / eg; }
;               u32x2 w1, w2; w1.x = cvt_pk_bf16(x1[0], x1[1]); w1.y = cvt_pk_bf16(x1[2], x1[3]); w2.x = cvt_pk_bf16(x2[0], x2[1]); w2.y = cvt_pk_bf16(x2[2], x2[3]);
;               *(LAS u32x2*)(T1 + i * 72 + d) = w1; *(LAS u32x2*)(T2 + i * 72 + d) = w2; } }
.LBB0_312:
	s_andn2_saveexec_b64 s[38:39], s[38:39]
	s_cbranch_execz .LBB0_314
	v_add_u32_e32 v16, v139, v133
	v_add_u32_e32 v126, v139, v133
	ds_read2_b32 v[128:129], v126 offset1:1
	ds_read2_b32 v[130:131], v126 offset0:2 offset1:3
	ds_read2_b32 v[174:175], v147 offset1:1
	ds_read2_b32 v[176:177], v147 offset0:2 offset1:3
	v_add_u32_e32 v127, 0x820, v147
	ds_read2_b32 v[178:179], v127 offset1:1
	v_add_u32_e32 v180, 0x828, v147
	ds_read2_b32 v[182:183], v180 offset1:1
	v_add_u32_e32 v181, 0x1040, v147
	ds_read2_b32 v[184:185], v181 offset1:1
	v_add_u32_e32 v186, 0x1048, v147
	ds_read2_b32 v[188:189], v186 offset1:1
	s_waitcnt lgkmcnt(0)
	v_pk_mul_f32 v[14:15], v[98:99], v[50:51]
	v_pk_mul_f32 v[6:7], v[98:99], v[6:7]
	v_pk_mul_f32 v[2:3], v[98:99], v[2:3]
	v_mul_f32_e32 v10, 0x3fb8aa3b, v128
	v_exp_f32_e32 v12, v10
	v_mul_f32_e32 v10, 0x3fb8aa3b, v129
	v_exp_f32_e32 v13, v10
	s_nop 0
	v_pk_mul_f32 v[10:11], v[14:15], v[12:13]
	v_rcp_f32_e32 v17, v13
	s_nop 0
	v_mul_f32_e32 v40, v15, v17
	v_cvt_pk_bf16_f32 v10, v10, v11
	v_rcp_f32_e32 v13, v12
	s_nop 0
	v_mul_f32_e32 v41, v14, v13
	v_pk_mul_f32 v[14:15], v[98:99], v[38:39]
	v_mul_f32_e32 v13, 0x3fb8aa3b, v131
	v_exp_f32_e32 v13, v13
	v_mul_f32_e32 v12, 0x3fb8aa3b, v130
	v_exp_f32_e32 v12, v12
	s_nop 0
	v_pk_mul_f32 v[16:17], v[14:15], v[12:13]
	v_rcp_f32_e32 v38, v13
	s_nop 0
	v_mul_f32_e32 v13, v15, v38
	v_cvt_pk_bf16_f32 v11, v16, v17
	v_rcp_f32_e32 v15, v12
	s_nop 0
	v_mul_f32_e32 v14, v14, v15
	v_cvt_pk_bf16_f32 v12, v41, v40
	v_cvt_pk_bf16_f32 v13, v14, v13
	ds_write_b64 v140, v[10:11]
	ds_write_b64 v141, v[12:13]
	v_pk_mul_f32 v[14:15], v[98:99], v[36:37]
	v_mul_f32_e32 v10, 0x3fb8aa3b, v174
	v_exp_f32_e32 v12, v10
	v_mul_f32_e32 v10, 0x3fb8aa3b, v175
	v_exp_f32_e32 v13, v10
	s_nop 0
	v_pk_mul_f32 v[10:11], v[14:15], v[12:13]
	v_rcp_f32_e32 v16, v13
	s_nop 0
	v_mul_f32_e32 v36, v15, v16
	v_cvt_pk_bf16_f32 v10, v10, v11
	v_rcp_f32_e32 v13, v12
	s_nop 0
	v_mul_f32_e32 v37, v14, v13
	v_pk_mul_f32 v[14:15], v[98:99], v[32:33]
	v_mul_f32_e32 v13, 0x3fb8aa3b, v177
	v_exp_f32_e32 v13, v13
	v_mul_f32_e32 v12, 0x3fb8aa3b, v176
	v_exp_f32_e32 v12, v12
	s_nop 0
	v_pk_mul_f32 v[16:17], v[14:15], v[12:13]
	v_rcp_f32_e32 v32, v13
	s_nop 0
	v_mul_f32_e32 v13, v15, v32
	v_cvt_pk_bf16_f32 v11, v16, v17
	v_rcp_f32_e32 v15, v12
	s_nop 0
	v_mul_f32_e32 v14, v14, v15
	v_cvt_pk_bf16_f32 v12, v37, v36
	v_cvt_pk_bf16_f32 v13, v14, v13
	ds_write_b64 v140, v[10:11] offset:1152
	ds_write_b64 v141, v[12:13] offset:1152
	v_add_u32_e32 v10, 0x820, v147
	v_pk_mul_f32 v[14:15], v[98:99], v[34:35]
	v_mul_f32_e32 v10, 0x3fb8aa3b, v178
	v_exp_f32_e32 v12, v10
	v_mul_f32_e32 v10, 0x3fb8aa3b, v179
	v_exp_f32_e32 v13, v10
	s_nop 0
	v_pk_mul_f32 v[10:11], v[14:15], v[12:13]
	v_rcp_f32_e32 v16, v13
	s_nop 0
	v_mul_f32_e32 v32, v15, v16
	v_cvt_pk_bf16_f32 v10, v10, v11
	v_rcp_f32_e32 v13, v12
	s_nop 0
	v_mul_f32_e32 v33, v14, v13
	v_add_u32_e32 v12, 0x828, v147
	v_pk_mul_f32 v[14:15], v[98:99], v[30:31]
	v_mul_f32_e32 v13, 0x3fb8aa3b, v183
	v_exp_f32_e32 v13, v13
	v_mul_f32_e32 v12, 0x3fb8aa3b, v182
	v_exp_f32_e32 v12, v12
	s_nop 0
	v_pk_mul_f32 v[16:17], v[14:15], v[12:13]
	v_rcp_f32_e32 v30, v13
	s_nop 0
	v_mul_f32_e32 v13, v15, v30
	v_cvt_pk_bf16_f32 v11, v16, v17
	v_rcp_f32_e32 v15, v12
	s_nop 0
	v_mul_f32_e32 v14, v14, v15
	v_cvt_pk_bf16_f32 v12, v33, v32
	v_cvt_pk_bf16_f32 v13, v14, v13
	ds_write_b64 v140, v[10:11] offset:2304
	ds_write_b64 v141, v[12:13] offset:2304
	v_add_u32_e32 v10, 0x1040, v147
	v_pk_mul_f32 v[14:15], v[98:99], v[28:29]
	v_mul_f32_e32 v10, 0x3fb8aa3b, v184
	v_exp_f32_e32 v12, v10
	v_mul_f32_e32 v10, 0x3fb8aa3b, v185
	v_exp_f32_e32 v13, v10
	s_nop 0
	v_pk_mul_f32 v[10:11], v[14:15], v[12:13]
	v_rcp_f32_e32 v16, v13
	s_nop 0
	v_mul_f32_e32 v28, v15, v16
	v_cvt_pk_bf16_f32 v10, v10, v11
	v_rcp_f32_e32 v13, v12
	s_nop 0
	v_mul_f32_e32 v29, v14, v13
	v_add_u32_e32 v12, 0x1048, v147
	v_pk_mul_f32 v[14:15], v[98:99], v[24:25]
	v_mul_f32_e32 v13, 0x3fb8aa3b, v189
	v_exp_f32_e32 v13, v13
	v_mul_f32_e32 v12, 0x3fb8aa3b, v188
	v_exp_f32_e32 v12, v12
	s_nop 0
	v_pk_mul_f32 v[16:17], v[14:15], v[12:13]
	v_rcp_f32_e32 v24, v13
	s_nop 0
	v_mul_f32_e32 v13, v15, v24
	v_cvt_pk_bf16_f32 v11, v16, v17
	v_rcp_f32_e32 v15, v12
	s_nop 0
	v_mul_f32_e32 v14, v14, v15
	v_cvt_pk_bf16_f32 v12, v29, v28
	v_cvt_pk_bf16_f32 v13, v14, v13
	ds_write_b64 v140, v[10:11] offset:3456
	ds_write_b64 v141, v[12:13] offset:3456
	v_add_u32_e32 v10, 0x1860, v147
	v_add_u32_e32 v126, 0x1860, v147
	ds_read2_b32 v[128:129], v126 offset1:1
	v_add_u32_e32 v127, 0x1868, v147
	ds_read2_b32 v[130:131], v127 offset1:1
	v_add_u32_e32 v174, 0x2080, v147
	ds_read2_b32 v[176:177], v174 offset1:1
	v_add_u32_e32 v175, 0x2088, v147
	ds_read2_b32 v[178:179], v175 offset1:1
	v_add_u32_e32 v180, 0x28a0, v147
	ds_read2_b32 v[182:183], v180 offset1:1
	v_add_u32_e32 v181, 0x28a8, v147
	ds_read2_b32 v[184:185], v181 offset1:1
	v_add_u32_e32 v186, 0x30c0, v147
	ds_read2_b32 v[188:189], v186 offset1:1
	v_add_u32_e32 v187, 0x30c8, v147
	ds_read2_b32 v[190:191], v187 offset1:1
	s_waitcnt lgkmcnt(0)
; #define LAS __attribute__((address_space(3)))
; __device__ __forceinline__ unsigned cvt_pk_bf16(float lo, float hi) { const f32x2 v = {lo, hi}; const bf16x2_t r = __builtin_convertvector(v, bf16x2_t); return __builtin_bit_cast(unsigned, r); }
; __device__ __forceinline__ void gla_c_tile(LAS unsigned char* lds, const GlaArgs& A, int tile, int tid) {
;     ...
;       if (cc < 128) { const int d = cc & 63; const bool isq = cc < 64; LAS bf16_t* T1 = isq ? QG : KR; LAS bf16_t* T2 = isq ? QR : KG; const float sc = isq ? 0.125f : 1.0f;
; #pragma unroll
;           for (int e = 0; e < 8; ++e) { const int i = i0 + 8 * e; f32x4 x1, x2;
; #pragma unroll
;               for (int q = 0; q < 4; ++q) { const float eg = __expf(GC[i * 65 + d + q]); const float x = o[e][q] * sc; x1[q] = x * eg; x2[q] = x / eg; }
;               u32x2 w1, w2; w1.x = cvt_pk_bf16(x1[0], x1[1]); w1.y = cvt_pk_bf16(x1[2], x1[3]); w2.x = cvt_pk_bf16(x2[0], x2[1]); w2.y = cvt_pk_bf16(x2[2], x2[3]);
;               *(LAS u32x2*)(T1 + i * 72 + d) = w1; *(LAS u32x2*)(T2 + i * 72 + d) = w2; } }
	v_pk_mul_f32 v[14:15], v[98:99], v[26:27]
	v_mul_f32_e32 v10, 0x3fb8aa3b, v128
	v_exp_f32_e32 v12, v10
	v_mul_f32_e32 v10, 0x3fb8aa3b, v129
	v_exp_f32_e32 v13, v10
	s_nop 0
	v_pk_mul_f32 v[10:11], v[14:15], v[12:13]
	v_rcp_f32_e32 v16, v13
	s_nop 0
	v_mul_f32_e32 v24, v15, v16
	v_cvt_pk_bf16_f32 v10, v10, v11
	v_rcp_f32_e32 v13, v12
	s_nop 0
	v_mul_f32_e32 v25, v14, v13
	v_add_u32_e32 v12, 0x1868, v147
	v_pk_mul_f32 v[14:15], v[98:99], v[22:23]
	v_mul_f32_e32 v13, 0x3fb8aa3b, v131
	v_exp_f32_e32 v13, v13
	v_mul_f32_e32 v12, 0x3fb8aa3b, v130
	v_exp_f32_e32 v12, v12
	s_nop 0
	v_pk_mul_f32 v[16:17], v[14:15], v[12:13]
	v_rcp_f32_e32 v22, v13
	s_nop 0
	v_mul_f32_e32 v13, v15, v22
	v_cvt_pk_bf16_f32 v11, v16, v17
	v_rcp_f32_e32 v15, v12
	s_nop 0
	v_mul_f32_e32 v14, v14, v15
	v_cvt_pk_bf16_f32 v12, v25, v24
	v_cvt_pk_bf16_f32 v13, v14, v13
	ds_write_b64 v140, v[10:11] offset:4608
	ds_write_b64 v141, v[12:13] offset:4608
	v_add_u32_e32 v10, 0x2080, v147
	v_pk_mul_f32 v[14:15], v[98:99], v[20:21]
	v_mul_f32_e32 v10, 0x3fb8aa3b, v176
	v_exp_f32_e32 v12, v10
	v_mul_f32_e32 v10, 0x3fb8aa3b, v177
	v_exp_f32_e32 v13, v10
	s_nop 0
	v_pk_mul_f32 v[10:11], v[14:15], v[12:13]
	v_rcp_f32_e32 v16, v13
	s_nop 0
	v_mul_f32_e32 v20, v15, v16
	v_cvt_pk_bf16_f32 v10, v10, v11
	v_rcp_f32_e32 v13, v12
	s_nop 0
	v_mul_f32_e32 v21, v14, v13
	v_add_u32_e32 v12, 0x2088, v147
	v_pk_mul_f32 v[14:15], v[98:99], v[18:19]
	v_mul_f32_e32 v13, 0x3fb8aa3b, v179
	v_exp_f32_e32 v13, v13
	v_mul_f32_e32 v12, 0x3fb8aa3b, v178
	v_exp_f32_e32 v12, v12
	s_nop 0
	v_pk_mul_f32 v[16:17], v[14:15], v[12:13]
	v_rcp_f32_e32 v18, v13
	s_nop 0
	v_mul_f32_e32 v13, v15, v18
	v_cvt_pk_bf16_f32 v11, v16, v17
	v_rcp_f32_e32 v15, v12
	s_nop 0
	v_mul_f32_e32 v14, v14, v15
	v_cvt_pk_bf16_f32 v12, v21, v20
	v_cvt_pk_bf16_f32 v13, v14, v13
	ds_write_b64 v140, v[10:11] offset:5760
	ds_write_b64 v141, v[12:13] offset:5760
	v_add_u32_e32 v10, 0x28a0, v147
	v_pk_mul_f32 v[12:13], v[98:99], v[8:9]
	v_mul_f32_e32 v8, 0x3fb8aa3b, v183
	v_exp_f32_e32 v11, v8
	v_mul_f32_e32 v10, 0x3fb8aa3b, v182
	v_exp_f32_e32 v10, v10
	s_nop 0
	v_pk_mul_f32 v[8:9], v[12:13], v[10:11]
	v_rcp_f32_e32 v14, v11
	s_nop 0
	v_mul_f32_e32 v14, v13, v14
	s_nop 0
	v_rcp_f32_e32 v11, v10
	s_nop 0
	v_mul_f32_e32 v15, v12, v11
	v_add_u32_e32 v10, 0x28a8, v147
	v_mul_f32_e32 v11, 0x3fb8aa3b, v185
	v_exp_f32_e32 v11, v11
	v_mul_f32_e32 v10, 0x3fb8aa3b, v184
	v_exp_f32_e32 v10, v10
	s_nop 0
	v_pk_mul_f32 v[12:13], v[6:7], v[10:11]
	v_rcp_f32_e32 v16, v11
	s_nop 0
	v_mul_f32_e32 v11, v7, v16
	s_nop 0
	v_rcp_f32_e32 v7, v10
	s_nop 0
	v_mul_f32_e32 v10, v6, v7
	v_cvt_pk_bf16_f32 v6, v8, v9
	v_cvt_pk_bf16_f32 v7, v12, v13
	v_cvt_pk_bf16_f32 v8, v15, v14
	v_cvt_pk_bf16_f32 v9, v10, v11
	ds_write_b64 v140, v[6:7] offset:6912
	ds_write_b64 v141, v[8:9] offset:6912
	v_add_u32_e32 v6, 0x30c0, v147
	v_pk_mul_f32 v[8:9], v[98:99], v[4:5]
	v_mul_f32_e32 v4, 0x3fb8aa3b, v189
	v_exp_f32_e32 v7, v4
	v_mul_f32_e32 v6, 0x3fb8aa3b, v188
	v_exp_f32_e32 v6, v6
	s_nop 0
	v_pk_mul_f32 v[4:5], v[8:9], v[6:7]
	v_rcp_f32_e32 v10, v7
	s_nop 0
	v_mul_f32_e32 v10, v9, v10
	s_nop 0
	v_rcp_f32_e32 v7, v6
	s_nop 0
	v_mul_f32_e32 v11, v8, v7
	v_add_u32_e32 v6, 0x30c8, v147
	v_mul_f32_e32 v7, 0x3fb8aa3b, v191
	v_exp_f32_e32 v7, v7
	v_mul_f32_e32 v6, 0x3fb8aa3b, v190
	v_exp_f32_e32 v6, v6
	s_nop 0
	v_pk_mul_f32 v[8:9], v[2:3], v[6:7]
	v_rcp_f32_e32 v12, v7
	s_nop 0
	v_mul_f32_e32 v7, v3, v12
	s_nop 0
	v_rcp_f32_e32 v3, v6
	s_nop 0
	v_mul_f32_e32 v6, v2, v3
	v_cvt_pk_bf16_f32 v2, v4, v5
	v_cvt_pk_bf16_f32 v3, v8, v9
	v_cvt_pk_bf16_f32 v4, v11, v10
	v_cvt_pk_bf16_f32 v5, v6, v7
	ds_write_b64 v140, v[2:3] offset:8064
	ds_write_b64 v141, v[4:5] offset:8064
